# relu^2 epilogue: dropped redundant canonicalizing v_max (bit-identical)
# baseline (speedup 1.0000x reference)
; __device__ __forceinline__ unsigned cvt_pk_bf16(float lo, float hi) { unsigned r; asm volatile("v_cvt_pk_bf16_f32 %0, %1, %2" : "=v"(r) : "v"(lo), "v"(hi)); return r; }
;     __device__ __forceinline__ void operator()(const f32x4 (&acc)[2][2][4][2], const Unit& u, int wr, int wc, int fr_, int fq_) const {
;     ...
; #pragma unroll
;         for (int ai = 0; ai < 2; ++ai)
; #pragma unroll
;             for (int m = 0; m < 4; ++m) rs[ai][m] = rstd[rowb + ai * HALF + m * 16];
; #pragma unroll
;         for (int ai = 0; ai < 2; ++ai)
; #pragma unroll
;             for (int m = 0; m < 4; ++m) { const int row = rowb + ai * HALF + m * 16; const float r1 = rs[ai][m];
;                 bf16_t* rowp = O + (size_t)row * ldc + col0;
; #pragma unroll
;                 for (int bj = 0; bj < 2; ++bj) { f32x4 v0 = acc[ai][bj][m][0] * r1, v1 = acc[ai][bj][m][1] * r1;
;                     if (act == 1) { v0 = __builtin_elementwise_max(v0, (f32x4){0.f, 0.f, 0.f, 0.f}); v1 = __builtin_elementwise_max(v1, (f32x4){0.f, 0.f, 0.f, 0.f}); v0 = v0 * v0; v1 = v1 * v1; }
;                     v0 = v0 * scale; v1 = v1 * scale;
;                     u32x4 w; w.x = cvt_pk_bf16(v0[0], v0[1]); w.y = cvt_pk_bf16(v0[2], v0[3]); w.z = cvt_pk_bf16(v1[0], v1[1]); w.w = cvt_pk_bf16(v1[2], v1[3]);
;                     *(u32x4*)(rowp + bj * HALF) = w; } }
.LBB0_2038:
	s_lshl_b32 s4, s4, 8
	v_mov_b32_e32 v139, v222
	s_add_i32 s4, s4, s51
	s_andn2_b64 vcc, exec, s[16:17]
	v_and_or_b32 v140, v139, 15, s4
	v_or_b32_e32 v158, 16, v140
	v_or_b32_e32 v154, 32, v140
	v_or_b32_e32 v150, 48, v140
	v_ashrrev_i32_e32 v141, 31, v140
	v_ashrrev_i32_e32 v159, 31, v158
	v_ashrrev_i32_e32 v155, 31, v154
	v_ashrrev_i32_e32 v151, 31, v150
	v_lshl_add_u64 v[162:163], v[140:141], 2, s[18:19]
	v_lshl_add_u64 v[142:143], v[158:159], 2, s[18:19]
	v_lshl_add_u64 v[144:145], v[154:155], 2, s[18:19]
	v_lshl_add_u64 v[146:147], v[150:151], 2, s[18:19]
	global_load_dword v160, v[162:163], off
	global_load_dword v156, v[142:143], off
	global_load_dword v152, v[144:145], off
	global_load_dword v148, v[146:147], off
	s_nop 0
	global_load_dword v146, v[162:163], off offset:512
	global_load_dword v144, v[162:163], off offset:576
	global_load_dword v142, v[162:163], off offset:640
	global_load_dword v138, v[162:163], off offset:704
	v_cndmask_b32_e64 v143, 0, 1, s[16:17]
	v_cmp_ne_u32_e64 s[4:5], 1, v143
	s_waitcnt vmcnt(0)
	v_pk_mul_f32 v[126:127], v[126:127], v[160:161] op_sel_hi:[1,0]
	v_pk_mul_f32 v[162:163], v[124:125], v[160:161] op_sel_hi:[1,0]
	v_pk_mul_f32 v[124:125], v[122:123], v[160:161] op_sel_hi:[1,0]
	v_pk_mul_f32 v[164:165], v[120:121], v[160:161] op_sel_hi:[1,0]
	s_cbranch_vccnz .LBB0_2040
	v_max_f32_e32 v122, 0, v126
	v_max_f32_e32 v120, 0, v162
	v_max_f32_e32 v123, 0, v127
	v_max_f32_e32 v121, 0, v163
	v_max_f32_e32 v165, 0, v165
	v_max_f32_e32 v125, 0, v125
	v_max_f32_e32 v124, 0, v124
	v_max_f32_e32 v164, 0, v164
	v_pk_mul_f32 v[126:127], v[122:123], v[122:123]
	v_pk_mul_f32 v[162:163], v[120:121], v[120:121]
	v_pk_mul_f32 v[124:125], v[124:125], v[124:125]
	v_pk_mul_f32 v[164:165], v[164:165], v[164:165]
.LBB0_2040:
	v_lshrrev_b32_e32 v120, 1, v139
	s_lshl_b32 s25, s34, 8
	v_and_or_b32 v120, v120, 24, s25
	v_or_b32_e32 v120, s53, v120
	v_lshlrev_b64 v[122:123], s61, v[140:141]
	v_ashrrev_i32_e32 v121, 31, v120
	v_lshl_add_u64 v[122:123], v[122:123], 1, s[12:13]
	v_lshl_add_u64 v[122:123], v[120:121], 1, v[122:123]
	v_pk_mul_f32 v[126:127], s[20:21], v[126:127]
	v_pk_mul_f32 v[162:163], s[10:11], v[162:163]
	v_pk_mul_f32 v[170:171], s[20:21], v[124:125]
	v_cvt_pk_bf16_f32 v124, v162, v163
	v_cvt_pk_bf16_f32 v125, v126, v127
	v_mov_b32_e32 v161, v160
	v_pk_mul_f32 v[164:165], s[10:11], v[164:165]
	v_pk_mul_f32 v[116:117], v[116:117], v[160:161]
	v_cvt_pk_bf16_f32 v126, v164, v165
	v_cvt_pk_bf16_f32 v127, v170, v171
	global_store_dwordx4 v[122:123], v[124:127], off
	v_pk_mul_f32 v[112:113], v[112:113], v[160:161]
	s_and_b64 vcc, exec, s[4:5]
	v_mov_b32_e32 v124, v160
	v_mov_b32_e32 v125, v160
	v_pk_mul_f32 v[118:119], v[118:119], v[124:125]
	v_pk_mul_f32 v[114:115], v[114:115], v[124:125]
	s_mov_b64 s[34:35], 9
	s_cbranch_vccnz .LBB0_2042
	v_max_f32_e32 v117, 0, v117
	v_max_f32_e32 v116, 0, v116
	v_max_f32_e32 v119, 0, v119
	v_max_f32_e32 v118, 0, v118
	v_max_f32_e32 v113, 0, v113
	v_max_f32_e32 v112, 0, v112
	v_max_f32_e32 v115, 0, v115
	v_max_f32_e32 v114, 0, v114
	v_pk_mul_f32 v[118:119], v[118:119], v[118:119]
	v_pk_mul_f32 v[116:117], v[116:117], v[116:117]
	v_pk_mul_f32 v[114:115], v[114:115], v[114:115]
	v_pk_mul_f32 v[112:113], v[112:113], v[112:113]
	s_mov_b64 s[34:35], 12
.LBB0_2042:
	v_pk_mul_f32 v[118:119], s[20:21], v[118:119]
	v_pk_mul_f32 v[116:117], s[10:11], v[116:117]
	v_pk_mul_f32 v[124:125], s[20:21], v[114:115]
	v_pk_mul_f32 v[114:115], s[10:11], v[112:113]
	v_cvt_pk_bf16_f32 v112, v116, v117
	v_cvt_pk_bf16_f32 v113, v118, v119
	v_readlane_b32 s66, v254, 31
	v_readlane_b32 s68, v254, 33
	v_readlane_b32 s70, v254, 35
	v_cvt_pk_bf16_f32 v114, v114, v115
	v_cvt_pk_bf16_f32 v115, v124, v125
	global_store_dwordx4 v[122:123], v[112:115], off offset:256
	v_pk_mul_f32 v[110:111], v[110:111], v[156:157] op_sel_hi:[1,0]
	v_pk_mul_f32 v[108:109], v[108:109], v[156:157] op_sel_hi:[1,0]
	v_pk_mul_f32 v[106:107], v[106:107], v[156:157] op_sel_hi:[1,0]
	s_and_b64 vcc, exec, s[4:5]
	v_pk_mul_f32 v[112:113], v[104:105], v[156:157] op_sel_hi:[1,0]
	v_readlane_b32 s67, v254, 32
	v_readlane_b32 s69, v254, 34
	v_readlane_b32 s71, v254, 36
	s_cbranch_vccnz .LBB0_2044
	v_max_f32_e32 v104, 0, v108
	v_max_f32_e32 v105, 0, v109
	v_max_f32_e32 v108, 0, v110
	v_max_f32_e32 v109, 0, v111
	v_max_f32_e32 v113, 0, v113
	v_max_f32_e32 v107, 0, v107
	v_max_f32_e32 v106, 0, v106
	v_max_f32_e32 v112, 0, v112
	v_pk_mul_f32 v[110:111], v[108:109], v[108:109]
	v_pk_mul_f32 v[108:109], v[104:105], v[104:105]
	v_pk_mul_f32 v[106:107], v[106:107], v[106:107]
	v_pk_mul_f32 v[112:113], v[112:113], v[112:113]
.LBB0_2044:
	v_lshlrev_b64 v[104:105], s34, v[158:159]
	v_lshl_add_u64 v[104:105], v[104:105], 1, s[12:13]
	v_lshl_add_u64 v[104:105], v[120:121], 1, v[104:105]
	v_pk_mul_f32 v[110:111], s[20:21], v[110:111]
	v_pk_mul_f32 v[108:109], s[10:11], v[108:109]
	v_pk_mul_f32 v[114:115], s[20:21], v[106:107]
	v_cvt_pk_bf16_f32 v106, v108, v109
	v_cvt_pk_bf16_f32 v107, v110, v111
	v_mov_b32_e32 v157, v156
	v_pk_mul_f32 v[112:113], s[10:11], v[112:113]
	v_pk_mul_f32 v[100:101], v[100:101], v[156:157]
	v_cvt_pk_bf16_f32 v108, v112, v113
	v_cvt_pk_bf16_f32 v109, v114, v115
	global_store_dwordx4 v[104:105], v[106:109], off
	v_pk_mul_f32 v[96:97], v[96:97], v[156:157]
	s_and_b64 vcc, exec, s[4:5]
	v_mov_b32_e32 v106, v156
	v_mov_b32_e32 v107, v156
	v_pk_mul_f32 v[102:103], v[102:103], v[106:107]
	v_pk_mul_f32 v[98:99], v[98:99], v[106:107]
	s_mov_b64 s[34:35], 9
	s_cbranch_vccnz .LBB0_2046
	v_max_f32_e32 v101, 0, v101
	v_max_f32_e32 v100, 0, v100
	v_max_f32_e32 v103, 0, v103
	v_max_f32_e32 v102, 0, v102
	v_max_f32_e32 v97, 0, v97
	v_max_f32_e32 v96, 0, v96
	v_max_f32_e32 v99, 0, v99
	v_max_f32_e32 v98, 0, v98
	v_pk_mul_f32 v[102:103], v[102:103], v[102:103]
	v_pk_mul_f32 v[100:101], v[100:101], v[100:101]
	v_pk_mul_f32 v[98:99], v[98:99], v[98:99]
	v_pk_mul_f32 v[96:97], v[96:97], v[96:97]
	s_mov_b64 s[34:35], 12
; __device__ __forceinline__ unsigned cvt_pk_bf16(float lo, float hi) { unsigned r; asm volatile("v_cvt_pk_bf16_f32 %0, %1, %2" : "=v"(r) : "v"(lo), "v"(hi)); return r; }
;     __device__ __forceinline__ void operator()(const f32x4 (&acc)[2][2][4][2], const Unit& u, int wr, int wc, int fr_, int fq_) const {
;     ...
; #pragma unroll
;         for (int ai = 0; ai < 2; ++ai)
; #pragma unroll
;             for (int m = 0; m < 4; ++m) { const int row = rowb + ai * HALF + m * 16; const float r1 = rs[ai][m];
;                 bf16_t* rowp = O + (size_t)row * ldc + col0;
; #pragma unroll
;                 for (int bj = 0; bj < 2; ++bj) { f32x4 v0 = acc[ai][bj][m][0] * r1, v1 = acc[ai][bj][m][1] * r1;
;                     if (act == 1) { v0 = __builtin_elementwise_max(v0, (f32x4){0.f, 0.f, 0.f, 0.f}); v1 = __builtin_elementwise_max(v1, (f32x4){0.f, 0.f, 0.f, 0.f}); v0 = v0 * v0; v1 = v1 * v1; }
;                     v0 = v0 * scale; v1 = v1 * scale;
;                     u32x4 w; w.x = cvt_pk_bf16(v0[0], v0[1]); w.y = cvt_pk_bf16(v0[2], v0[3]); w.z = cvt_pk_bf16(v1[0], v1[1]); w.w = cvt_pk_bf16(v1[2], v1[3]);
;                     *(u32x4*)(rowp + bj * HALF) = w; } }
.LBB0_2046:
	v_pk_mul_f32 v[102:103], s[20:21], v[102:103]
	v_pk_mul_f32 v[100:101], s[10:11], v[100:101]
	v_pk_mul_f32 v[106:107], s[20:21], v[98:99]
	v_pk_mul_f32 v[98:99], s[10:11], v[96:97]
	v_cvt_pk_bf16_f32 v96, v100, v101
	v_cvt_pk_bf16_f32 v97, v102, v103
	v_pk_mul_f32 v[94:95], v[94:95], v[152:153] op_sel_hi:[1,0]
	v_cvt_pk_bf16_f32 v98, v98, v99
	v_cvt_pk_bf16_f32 v99, v106, v107
	global_store_dwordx4 v[104:105], v[96:99], off offset:256
	v_pk_mul_f32 v[92:93], v[92:93], v[152:153] op_sel_hi:[1,0]
	v_pk_mul_f32 v[90:91], v[90:91], v[152:153] op_sel_hi:[1,0]
	s_and_b64 vcc, exec, s[4:5]
	v_pk_mul_f32 v[96:97], v[88:89], v[152:153] op_sel_hi:[1,0]
	s_cbranch_vccnz .LBB0_2048
	v_max_f32_e32 v88, 0, v92
	v_max_f32_e32 v89, 0, v93
	v_max_f32_e32 v92, 0, v94
	v_max_f32_e32 v93, 0, v95
	v_max_f32_e32 v97, 0, v97
	v_max_f32_e32 v91, 0, v91
	v_max_f32_e32 v90, 0, v90
	v_max_f32_e32 v96, 0, v96
	v_pk_mul_f32 v[94:95], v[92:93], v[92:93]
	v_pk_mul_f32 v[92:93], v[88:89], v[88:89]
	v_pk_mul_f32 v[90:91], v[90:91], v[90:91]
	v_pk_mul_f32 v[96:97], v[96:97], v[96:97]
.LBB0_2048:
	v_lshlrev_b64 v[88:89], s34, v[154:155]
	v_lshl_add_u64 v[88:89], v[88:89], 1, s[12:13]
	v_lshl_add_u64 v[88:89], v[120:121], 1, v[88:89]
	v_pk_mul_f32 v[94:95], s[20:21], v[94:95]
	v_pk_mul_f32 v[92:93], s[10:11], v[92:93]
	v_pk_mul_f32 v[98:99], s[20:21], v[90:91]
	v_cvt_pk_bf16_f32 v90, v92, v93
	v_cvt_pk_bf16_f32 v91, v94, v95
	v_mov_b32_e32 v153, v152
	v_pk_mul_f32 v[96:97], s[10:11], v[96:97]
	v_pk_mul_f32 v[84:85], v[84:85], v[152:153]
	v_cvt_pk_bf16_f32 v92, v96, v97
	v_cvt_pk_bf16_f32 v93, v98, v99
	global_store_dwordx4 v[88:89], v[90:93], off
	v_pk_mul_f32 v[80:81], v[80:81], v[152:153]
	s_and_b64 vcc, exec, s[4:5]
	v_mov_b32_e32 v90, v152
	v_mov_b32_e32 v91, v152
	v_pk_mul_f32 v[86:87], v[86:87], v[90:91]
	v_pk_mul_f32 v[82:83], v[82:83], v[90:91]
	s_mov_b64 s[34:35], 9
	s_cbranch_vccnz .LBB0_2050
	v_max_f32_e32 v85, 0, v85
	v_max_f32_e32 v84, 0, v84
	v_max_f32_e32 v87, 0, v87
	v_max_f32_e32 v86, 0, v86
	v_max_f32_e32 v81, 0, v81
	v_max_f32_e32 v80, 0, v80
	v_max_f32_e32 v83, 0, v83
	v_max_f32_e32 v82, 0, v82
	v_pk_mul_f32 v[86:87], v[86:87], v[86:87]
	v_pk_mul_f32 v[84:85], v[84:85], v[84:85]
	v_pk_mul_f32 v[82:83], v[82:83], v[82:83]
	v_pk_mul_f32 v[80:81], v[80:81], v[80:81]
	s_mov_b64 s[34:35], 12
.LBB0_2050:
	v_pk_mul_f32 v[86:87], s[20:21], v[86:87]
	v_pk_mul_f32 v[84:85], s[10:11], v[84:85]
	v_pk_mul_f32 v[90:91], s[20:21], v[82:83]
	v_pk_mul_f32 v[82:83], s[10:11], v[80:81]
	v_cvt_pk_bf16_f32 v80, v84, v85
	v_cvt_pk_bf16_f32 v81, v86, v87
	v_pk_mul_f32 v[78:79], v[78:79], v[148:149] op_sel_hi:[1,0]
	v_cvt_pk_bf16_f32 v82, v82, v83
	v_cvt_pk_bf16_f32 v83, v90, v91
	global_store_dwordx4 v[88:89], v[80:83], off offset:256
	v_pk_mul_f32 v[76:77], v[76:77], v[148:149] op_sel_hi:[1,0]
	v_pk_mul_f32 v[74:75], v[74:75], v[148:149] op_sel_hi:[1,0]
	s_and_b64 vcc, exec, s[4:5]
	v_pk_mul_f32 v[80:81], v[72:73], v[148:149] op_sel_hi:[1,0]
	s_cbranch_vccnz .LBB0_2052
	v_max_f32_e32 v72, 0, v76
	v_max_f32_e32 v73, 0, v77
	v_max_f32_e32 v76, 0, v78
	v_max_f32_e32 v77, 0, v79
	v_max_f32_e32 v81, 0, v81
	v_max_f32_e32 v75, 0, v75
	v_max_f32_e32 v74, 0, v74
	v_max_f32_e32 v80, 0, v80
	v_pk_mul_f32 v[78:79], v[76:77], v[76:77]
	v_pk_mul_f32 v[76:77], v[72:73], v[72:73]
	v_pk_mul_f32 v[74:75], v[74:75], v[74:75]
	v_pk_mul_f32 v[80:81], v[80:81], v[80:81]
.LBB0_2052:
	v_lshlrev_b64 v[72:73], s34, v[150:151]
	v_lshl_add_u64 v[72:73], v[72:73], 1, s[12:13]
	v_lshl_add_u64 v[72:73], v[120:121], 1, v[72:73]
	v_pk_mul_f32 v[78:79], s[20:21], v[78:79]
	v_pk_mul_f32 v[76:77], s[10:11], v[76:77]
	v_pk_mul_f32 v[82:83], s[20:21], v[74:75]
	v_cvt_pk_bf16_f32 v74, v76, v77
	v_cvt_pk_bf16_f32 v75, v78, v79
	v_mov_b32_e32 v149, v148
	v_pk_mul_f32 v[80:81], s[10:11], v[80:81]
	v_pk_mul_f32 v[68:69], v[68:69], v[148:149]
	v_cvt_pk_bf16_f32 v76, v80, v81
	v_cvt_pk_bf16_f32 v77, v82, v83
	global_store_dwordx4 v[72:73], v[74:77], off
	v_pk_mul_f32 v[64:65], v[64:65], v[148:149]
	s_and_b64 vcc, exec, s[4:5]
	v_mov_b32_e32 v74, v148
	v_mov_b32_e32 v75, v148
	v_pk_mul_f32 v[70:71], v[70:71], v[74:75]
	v_pk_mul_f32 v[66:67], v[66:67], v[74:75]
	s_mov_b64 s[34:35], 9
	s_cbranch_vccnz .LBB0_2054
	v_max_f32_e32 v69, 0, v69
	v_max_f32_e32 v68, 0, v68
	v_max_f32_e32 v71, 0, v71
	v_max_f32_e32 v70, 0, v70
	v_max_f32_e32 v65, 0, v65
	v_max_f32_e32 v64, 0, v64
	v_max_f32_e32 v67, 0, v67
	v_max_f32_e32 v66, 0, v66
	v_pk_mul_f32 v[70:71], v[70:71], v[70:71]
	v_pk_mul_f32 v[68:69], v[68:69], v[68:69]
	v_pk_mul_f32 v[66:67], v[66:67], v[66:67]
	v_pk_mul_f32 v[64:65], v[64:65], v[64:65]
	s_mov_b64 s[34:35], 12
.LBB0_2054:
	v_pk_mul_f32 v[70:71], s[20:21], v[70:71]
	v_pk_mul_f32 v[68:69], s[10:11], v[68:69]
	v_pk_mul_f32 v[74:75], s[20:21], v[66:67]
	v_pk_mul_f32 v[66:67], s[10:11], v[64:65]
	v_cvt_pk_bf16_f32 v64, v68, v69
	v_cvt_pk_bf16_f32 v65, v70, v71
	v_pk_mul_f32 v[62:63], v[62:63], v[146:147] op_sel_hi:[1,0]
	v_cvt_pk_bf16_f32 v66, v66, v67
	v_cvt_pk_bf16_f32 v67, v74, v75
	global_store_dwordx4 v[72:73], v[64:67], off offset:256
	v_pk_mul_f32 v[60:61], v[60:61], v[146:147] op_sel_hi:[1,0]
	v_pk_mul_f32 v[58:59], v[58:59], v[146:147] op_sel_hi:[1,0]
	s_and_b64 vcc, exec, s[4:5]
	v_pk_mul_f32 v[64:65], v[56:57], v[146:147] op_sel_hi:[1,0]
	s_cbranch_vccnz .LBB0_2056
	v_max_f32_e32 v56, 0, v60
	v_max_f32_e32 v57, 0, v61
	v_max_f32_e32 v60, 0, v62
	v_max_f32_e32 v61, 0, v63
	v_max_f32_e32 v65, 0, v65
	v_max_f32_e32 v59, 0, v59
	v_max_f32_e32 v58, 0, v58
	v_max_f32_e32 v64, 0, v64
	v_pk_mul_f32 v[62:63], v[60:61], v[60:61]
	v_pk_mul_f32 v[60:61], v[56:57], v[56:57]
	v_pk_mul_f32 v[58:59], v[58:59], v[58:59]
	v_pk_mul_f32 v[64:65], v[64:65], v[64:65]
; __device__ __forceinline__ unsigned cvt_pk_bf16(float lo, float hi) { unsigned r; asm volatile("v_cvt_pk_bf16_f32 %0, %1, %2" : "=v"(r) : "v"(lo), "v"(hi)); return r; }
;     __device__ __forceinline__ void operator()(const f32x4 (&acc)[2][2][4][2], const Unit& u, int wr, int wc, int fr_, int fq_) const {
;     ...
; #pragma unroll
;         for (int ai = 0; ai < 2; ++ai)
; #pragma unroll
;             for (int m = 0; m < 4; ++m) { const int row = rowb + ai * HALF + m * 16; const float r1 = rs[ai][m];
;                 bf16_t* rowp = O + (size_t)row * ldc + col0;
; #pragma unroll
;                 for (int bj = 0; bj < 2; ++bj) { f32x4 v0 = acc[ai][bj][m][0] * r1, v1 = acc[ai][bj][m][1] * r1;
;                     if (act == 1) { v0 = __builtin_elementwise_max(v0, (f32x4){0.f, 0.f, 0.f, 0.f}); v1 = __builtin_elementwise_max(v1, (f32x4){0.f, 0.f, 0.f, 0.f}); v0 = v0 * v0; v1 = v1 * v1; }
;                     v0 = v0 * scale; v1 = v1 * scale;
;                     u32x4 w; w.x = cvt_pk_bf16(v0[0], v0[1]); w.y = cvt_pk_bf16(v0[2], v0[3]); w.z = cvt_pk_bf16(v1[0], v1[1]); w.w = cvt_pk_bf16(v1[2], v1[3]);
;                     *(u32x4*)(rowp + bj * HALF) = w; } }
.LBB0_2056:
	v_add_u32_e32 v56, 0x80, v140
	v_ashrrev_i32_e32 v57, 31, v56
	v_lshlrev_b64 v[56:57], s34, v[56:57]
	v_lshl_add_u64 v[56:57], v[56:57], 1, s[12:13]
	v_lshl_add_u64 v[56:57], v[120:121], 1, v[56:57]
	v_pk_mul_f32 v[62:63], s[20:21], v[62:63]
	v_pk_mul_f32 v[60:61], s[10:11], v[60:61]
	v_pk_mul_f32 v[66:67], s[20:21], v[58:59]
	v_cvt_pk_bf16_f32 v58, v60, v61
	v_cvt_pk_bf16_f32 v59, v62, v63
	v_mov_b32_e32 v147, v146
	v_pk_mul_f32 v[64:65], s[10:11], v[64:65]
	v_pk_mul_f32 v[52:53], v[52:53], v[146:147]
	v_cvt_pk_bf16_f32 v60, v64, v65
	v_cvt_pk_bf16_f32 v61, v66, v67
	global_store_dwordx4 v[56:57], v[58:61], off
	v_pk_mul_f32 v[48:49], v[48:49], v[146:147]
	s_and_b64 vcc, exec, s[4:5]
	v_mov_b32_e32 v58, v146
	v_mov_b32_e32 v59, v146
	v_pk_mul_f32 v[54:55], v[54:55], v[58:59]
	v_pk_mul_f32 v[50:51], v[50:51], v[58:59]
	s_mov_b64 s[34:35], 9
	s_cbranch_vccnz .LBB0_2058
	v_max_f32_e32 v53, 0, v53
	v_max_f32_e32 v52, 0, v52
	v_max_f32_e32 v55, 0, v55
	v_max_f32_e32 v54, 0, v54
	v_max_f32_e32 v49, 0, v49
	v_max_f32_e32 v48, 0, v48
	v_max_f32_e32 v51, 0, v51
	v_max_f32_e32 v50, 0, v50
	v_pk_mul_f32 v[54:55], v[54:55], v[54:55]
	v_pk_mul_f32 v[52:53], v[52:53], v[52:53]
	v_pk_mul_f32 v[50:51], v[50:51], v[50:51]
	v_pk_mul_f32 v[48:49], v[48:49], v[48:49]
	s_mov_b64 s[34:35], 12
.LBB0_2058:
	v_pk_mul_f32 v[54:55], s[20:21], v[54:55]
	v_pk_mul_f32 v[52:53], s[10:11], v[52:53]
	v_pk_mul_f32 v[58:59], s[20:21], v[50:51]
	v_pk_mul_f32 v[50:51], s[10:11], v[48:49]
	v_cvt_pk_bf16_f32 v48, v52, v53
	v_cvt_pk_bf16_f32 v49, v54, v55
	v_pk_mul_f32 v[46:47], v[46:47], v[144:145] op_sel_hi:[1,0]
	v_cvt_pk_bf16_f32 v50, v50, v51
	v_cvt_pk_bf16_f32 v51, v58, v59
	global_store_dwordx4 v[56:57], v[48:51], off offset:256
	v_pk_mul_f32 v[44:45], v[44:45], v[144:145] op_sel_hi:[1,0]
	v_pk_mul_f32 v[42:43], v[42:43], v[144:145] op_sel_hi:[1,0]
	s_and_b64 vcc, exec, s[4:5]
	v_pk_mul_f32 v[48:49], v[40:41], v[144:145] op_sel_hi:[1,0]
	s_cbranch_vccnz .LBB0_2060
	v_max_f32_e32 v40, 0, v44
	v_max_f32_e32 v41, 0, v45
	v_max_f32_e32 v44, 0, v46
	v_max_f32_e32 v45, 0, v47
	v_max_f32_e32 v49, 0, v49
	v_max_f32_e32 v43, 0, v43
	v_max_f32_e32 v42, 0, v42
	v_max_f32_e32 v48, 0, v48
	v_pk_mul_f32 v[46:47], v[44:45], v[44:45]
	v_pk_mul_f32 v[44:45], v[40:41], v[40:41]
	v_pk_mul_f32 v[42:43], v[42:43], v[42:43]
	v_pk_mul_f32 v[48:49], v[48:49], v[48:49]
.LBB0_2060:
	v_add_u32_e32 v40, 0x90, v140
	v_ashrrev_i32_e32 v41, 31, v40
	v_lshlrev_b64 v[40:41], s34, v[40:41]
	v_lshl_add_u64 v[40:41], v[40:41], 1, s[12:13]
	v_lshl_add_u64 v[40:41], v[120:121], 1, v[40:41]
	v_pk_mul_f32 v[46:47], s[20:21], v[46:47]
	v_pk_mul_f32 v[44:45], s[10:11], v[44:45]
	v_pk_mul_f32 v[50:51], s[20:21], v[42:43]
	v_cvt_pk_bf16_f32 v42, v44, v45
	v_cvt_pk_bf16_f32 v43, v46, v47
	v_mov_b32_e32 v145, v144
	v_pk_mul_f32 v[48:49], s[10:11], v[48:49]
	v_pk_mul_f32 v[36:37], v[36:37], v[144:145]
	v_cvt_pk_bf16_f32 v44, v48, v49
	v_cvt_pk_bf16_f32 v45, v50, v51
	global_store_dwordx4 v[40:41], v[42:45], off
	v_pk_mul_f32 v[32:33], v[32:33], v[144:145]
	s_and_b64 vcc, exec, s[4:5]
	v_mov_b32_e32 v42, v144
	v_mov_b32_e32 v43, v144
	v_pk_mul_f32 v[38:39], v[38:39], v[42:43]
	v_pk_mul_f32 v[34:35], v[34:35], v[42:43]
	s_mov_b64 s[34:35], 9
	s_cbranch_vccnz .LBB0_2062
	v_max_f32_e32 v37, 0, v37
	v_max_f32_e32 v36, 0, v36
	v_max_f32_e32 v39, 0, v39
	v_max_f32_e32 v38, 0, v38
	v_max_f32_e32 v33, 0, v33
	v_max_f32_e32 v32, 0, v32
	v_max_f32_e32 v35, 0, v35
	v_max_f32_e32 v34, 0, v34
	v_pk_mul_f32 v[38:39], v[38:39], v[38:39]
	v_pk_mul_f32 v[36:37], v[36:37], v[36:37]
	v_pk_mul_f32 v[34:35], v[34:35], v[34:35]
	v_pk_mul_f32 v[32:33], v[32:33], v[32:33]
	s_mov_b64 s[34:35], 12
; __device__ __forceinline__ unsigned cvt_pk_bf16(float lo, float hi) { unsigned r; asm volatile("v_cvt_pk_bf16_f32 %0, %1, %2" : "=v"(r) : "v"(lo), "v"(hi)); return r; }
;     __device__ __forceinline__ void operator()(const f32x4 (&acc)[2][2][4][2], const Unit& u, int wr, int wc, int fr_, int fq_) const {
;     ...
; #pragma unroll
;         for (int ai = 0; ai < 2; ++ai)
; #pragma unroll
;             for (int m = 0; m < 4; ++m) { const int row = rowb + ai * HALF + m * 16; const float r1 = rs[ai][m];
;                 bf16_t* rowp = O + (size_t)row * ldc + col0;
; #pragma unroll
;                 for (int bj = 0; bj < 2; ++bj) { f32x4 v0 = acc[ai][bj][m][0] * r1, v1 = acc[ai][bj][m][1] * r1;
;                     if (act == 1) { v0 = __builtin_elementwise_max(v0, (f32x4){0.f, 0.f, 0.f, 0.f}); v1 = __builtin_elementwise_max(v1, (f32x4){0.f, 0.f, 0.f, 0.f}); v0 = v0 * v0; v1 = v1 * v1; }
;                     v0 = v0 * scale; v1 = v1 * scale;
;                     u32x4 w; w.x = cvt_pk_bf16(v0[0], v0[1]); w.y = cvt_pk_bf16(v0[2], v0[3]); w.z = cvt_pk_bf16(v1[0], v1[1]); w.w = cvt_pk_bf16(v1[2], v1[3]);
;                     *(u32x4*)(rowp + bj * HALF) = w; } }
.LBB0_2062:
	v_pk_mul_f32 v[38:39], s[20:21], v[38:39]
	v_pk_mul_f32 v[36:37], s[10:11], v[36:37]
	v_pk_mul_f32 v[42:43], s[20:21], v[34:35]
	v_pk_mul_f32 v[34:35], s[10:11], v[32:33]
	v_cvt_pk_bf16_f32 v32, v36, v37
	v_cvt_pk_bf16_f32 v33, v38, v39
	v_pk_mul_f32 v[30:31], v[30:31], v[142:143] op_sel_hi:[1,0]
	v_cvt_pk_bf16_f32 v34, v34, v35
	v_cvt_pk_bf16_f32 v35, v42, v43
	global_store_dwordx4 v[40:41], v[32:35], off offset:256
	v_pk_mul_f32 v[28:29], v[28:29], v[142:143] op_sel_hi:[1,0]
	v_pk_mul_f32 v[26:27], v[26:27], v[142:143] op_sel_hi:[1,0]
	s_and_b64 vcc, exec, s[4:5]
	v_pk_mul_f32 v[32:33], v[24:25], v[142:143] op_sel_hi:[1,0]
	s_cbranch_vccnz .LBB0_2064
	v_max_f32_e32 v24, 0, v28
	v_max_f32_e32 v25, 0, v29
	v_max_f32_e32 v28, 0, v30
	v_max_f32_e32 v29, 0, v31
	v_max_f32_e32 v33, 0, v33
	v_max_f32_e32 v27, 0, v27
	v_max_f32_e32 v26, 0, v26
	v_max_f32_e32 v32, 0, v32
	v_pk_mul_f32 v[30:31], v[28:29], v[28:29]
	v_pk_mul_f32 v[28:29], v[24:25], v[24:25]
	v_pk_mul_f32 v[26:27], v[26:27], v[26:27]
	v_pk_mul_f32 v[32:33], v[32:33], v[32:33]
.LBB0_2064:
	v_add_u32_e32 v24, 0xa0, v140
	v_ashrrev_i32_e32 v25, 31, v24
	v_lshlrev_b64 v[24:25], s34, v[24:25]
	v_lshl_add_u64 v[24:25], v[24:25], 1, s[12:13]
	v_lshl_add_u64 v[24:25], v[120:121], 1, v[24:25]
	v_pk_mul_f32 v[30:31], s[20:21], v[30:31]
	v_pk_mul_f32 v[28:29], s[10:11], v[28:29]
	v_pk_mul_f32 v[34:35], s[20:21], v[26:27]
	v_cvt_pk_bf16_f32 v26, v28, v29
	v_cvt_pk_bf16_f32 v27, v30, v31
	v_mov_b32_e32 v143, v142
	v_pk_mul_f32 v[32:33], s[10:11], v[32:33]
	v_pk_mul_f32 v[20:21], v[20:21], v[142:143]
	v_cvt_pk_bf16_f32 v28, v32, v33
	v_cvt_pk_bf16_f32 v29, v34, v35
	global_store_dwordx4 v[24:25], v[26:29], off
	v_pk_mul_f32 v[16:17], v[16:17], v[142:143]
	s_and_b64 vcc, exec, s[4:5]
	v_mov_b32_e32 v26, v142
	v_mov_b32_e32 v27, v142
	v_pk_mul_f32 v[22:23], v[22:23], v[26:27]
	v_pk_mul_f32 v[18:19], v[18:19], v[26:27]
	s_mov_b64 s[34:35], 9
	s_cbranch_vccnz .LBB0_2066
	v_max_f32_e32 v21, 0, v21
	v_max_f32_e32 v20, 0, v20
	v_max_f32_e32 v23, 0, v23
	v_max_f32_e32 v22, 0, v22
	v_max_f32_e32 v17, 0, v17
	v_max_f32_e32 v16, 0, v16
	v_max_f32_e32 v19, 0, v19
	v_max_f32_e32 v18, 0, v18
	v_pk_mul_f32 v[22:23], v[22:23], v[22:23]
	v_pk_mul_f32 v[20:21], v[20:21], v[20:21]
	v_pk_mul_f32 v[18:19], v[18:19], v[18:19]
	v_pk_mul_f32 v[16:17], v[16:17], v[16:17]
	s_mov_b64 s[34:35], 12
.LBB0_2066:
	v_pk_mul_f32 v[22:23], s[20:21], v[22:23]
	v_pk_mul_f32 v[20:21], s[10:11], v[20:21]
	v_pk_mul_f32 v[26:27], s[20:21], v[18:19]
	v_pk_mul_f32 v[18:19], s[10:11], v[16:17]
	v_cvt_pk_bf16_f32 v16, v20, v21
	v_cvt_pk_bf16_f32 v17, v22, v23
	v_pk_mul_f32 v[14:15], v[14:15], v[138:139] op_sel_hi:[1,0]
	v_cvt_pk_bf16_f32 v18, v18, v19
	v_cvt_pk_bf16_f32 v19, v26, v27
	global_store_dwordx4 v[24:25], v[16:19], off offset:256
	v_pk_mul_f32 v[12:13], v[12:13], v[138:139] op_sel_hi:[1,0]
	v_pk_mul_f32 v[10:11], v[10:11], v[138:139] op_sel_hi:[1,0]
	s_and_b64 vcc, exec, s[4:5]
	v_pk_mul_f32 v[16:17], v[8:9], v[138:139] op_sel_hi:[1,0]
	s_cbranch_vccnz .LBB0_2068
	v_max_f32_e32 v8, 0, v12
	v_max_f32_e32 v9, 0, v13
	v_max_f32_e32 v12, 0, v14
	v_max_f32_e32 v13, 0, v15
	v_max_f32_e32 v17, 0, v17
	v_max_f32_e32 v11, 0, v11
	v_max_f32_e32 v10, 0, v10
	v_max_f32_e32 v16, 0, v16
	v_pk_mul_f32 v[14:15], v[12:13], v[12:13]
	v_pk_mul_f32 v[12:13], v[8:9], v[8:9]
	v_pk_mul_f32 v[10:11], v[10:11], v[10:11]
	v_pk_mul_f32 v[16:17], v[16:17], v[16:17]
.LBB0_2068:
	v_add_u32_e32 v8, 0xb0, v140
	v_ashrrev_i32_e32 v9, 31, v8
	v_lshlrev_b64 v[8:9], s34, v[8:9]
	v_lshl_add_u64 v[8:9], v[8:9], 1, s[12:13]
	v_lshl_add_u64 v[8:9], v[120:121], 1, v[8:9]
	v_pk_mul_f32 v[14:15], s[20:21], v[14:15]
	v_pk_mul_f32 v[12:13], s[10:11], v[12:13]
	v_pk_mul_f32 v[18:19], s[20:21], v[10:11]
	v_cvt_pk_bf16_f32 v10, v12, v13
	v_cvt_pk_bf16_f32 v11, v14, v15
	v_mov_b32_e32 v139, v138
	v_pk_mul_f32 v[16:17], s[10:11], v[16:17]
	v_pk_mul_f32 v[4:5], v[4:5], v[138:139]
	v_cvt_pk_bf16_f32 v12, v16, v17
	v_cvt_pk_bf16_f32 v13, v18, v19
	global_store_dwordx4 v[8:9], v[10:13], off
	s_and_b64 vcc, exec, s[4:5]
	v_pk_mul_f32 v[0:1], v[0:1], v[138:139]
	v_mov_b32_e32 v10, v138
	v_mov_b32_e32 v11, v138
	v_pk_mul_f32 v[6:7], v[6:7], v[10:11]
	v_pk_mul_f32 v[2:3], v[2:3], v[10:11]
	s_cbranch_vccnz .LBB0_2070
	v_max_f32_e32 v5, 0, v5
	v_max_f32_e32 v4, 0, v4
	v_max_f32_e32 v7, 0, v7
	v_max_f32_e32 v6, 0, v6
	v_max_f32_e32 v1, 0, v1
	v_max_f32_e32 v0, 0, v0
	v_max_f32_e32 v3, 0, v3
	v_max_f32_e32 v2, 0, v2
	v_pk_mul_f32 v[6:7], v[6:7], v[6:7]
	v_pk_mul_f32 v[4:5], v[4:5], v[4:5]
	v_pk_mul_f32 v[2:3], v[2:3], v[2:3]
	v_pk_mul_f32 v[0:1], v[0:1], v[0:1]
